# attention loops: row-max tree reduces the earlier-finished accumulator first (fills the MFMA result wait), all three-input max (16 ops), stale s_nop removed in A loops
# speedup vs baseline: 1.0119x; 1.0017x over previous
.LBB0_934:
	s_or_b64 exec, exec, s[8:9]
	v_add3_u32 v64, s18, v190, v168
	ds_read_b128 v[32:35], v64
	ds_read_b128 v[36:39], v64 offset:0x1a00
	ds_read_b128 v[40:43], v64 offset:32
	ds_read_b128 v[44:47], v64 offset:0x1a20
	ds_read_b128 v[136:139], v64 offset:64
	ds_read_b128 v[140:143], v64 offset:0x1a40
	ds_read_b128 v[144:147], v64 offset:96
	ds_read_b128 v[148:151], v64 offset:0x1a60
	ds_read_b128 v[152:155], v64 offset:128
	ds_read_b128 v[156:159], v64 offset:0x1a80
	ds_read_b128 v[206:209], v64 offset:160
	ds_read_b128 v[160:163], v64 offset:0x1aa0
	s_nop 0
	s_waitcnt lgkmcnt(11)
	v_mfma_f32_32x32x16_bf16 v[80:95], v[32:35], v[116:119], v[48:63]
	v_add_u32_e32 v32, s18, v191
	v_add3_u32 v32, v32, v189, s87
	s_waitcnt lgkmcnt(10)
	v_mfma_f32_32x32x16_bf16 v[64:79], v[36:39], v[116:119], v[48:63]
	s_waitcnt lgkmcnt(9)
	v_mfma_f32_32x32x16_bf16 v[80:95], v[40:43], v[112:115], v[80:95]
	s_waitcnt lgkmcnt(8)
	v_mfma_f32_32x32x16_bf16 v[64:79], v[44:47], v[112:115], v[64:79]
	s_waitcnt lgkmcnt(7)
	v_mfma_f32_32x32x16_bf16 v[80:95], v[136:139], v[108:111], v[80:95]
	s_waitcnt lgkmcnt(6)
	v_mfma_f32_32x32x16_bf16 v[64:79], v[140:143], v[108:111], v[64:79]
	s_waitcnt lgkmcnt(5)
	v_mfma_f32_32x32x16_bf16 v[80:95], v[144:147], v[104:107], v[80:95]
	s_waitcnt lgkmcnt(4)
	v_mfma_f32_32x32x16_bf16 v[64:79], v[148:151], v[104:107], v[64:79]
	s_waitcnt lgkmcnt(3)
	v_mfma_f32_32x32x16_bf16 v[80:95], v[152:155], v[100:103], v[80:95]
	s_waitcnt lgkmcnt(2)
	v_mfma_f32_32x32x16_bf16 v[64:79], v[156:159], v[100:103], v[64:79]
	s_waitcnt lgkmcnt(0)
	v_mfma_f32_32x32x16_bf16 v[64:79], v[160:163], v[96:99], v[64:79]
	ds_read_b64 v[164:165], v32
	ds_read_b64 v[166:167], v32 offset:16
	ds_read_b64 v[160:161], v32 offset:32
	ds_read_b64 v[162:163], v32 offset:48
	ds_read_b64 v[156:157], v32 offset:64
	ds_read_b64 v[158:159], v32 offset:80
	ds_read_b64 v[152:153], v32 offset:96
	ds_read_b64 v[154:155], v32 offset:112
	ds_read_b64 v[148:149], v32 offset:0x1100
	ds_read_b64 v[150:151], v32 offset:0x1110
	ds_read_b64 v[144:145], v32 offset:0x1120
	ds_read_b64 v[146:147], v32 offset:0x1130
	ds_read_b64 v[140:141], v32 offset:0x1140
	ds_read_b64 v[142:143], v32 offset:0x1150
	ds_read_b64 v[136:137], v32 offset:0x1160
	ds_read_b64 v[138:139], v32 offset:0x1170
	v_mfma_f32_32x32x16_bf16 v[80:95], v[206:209], v[96:99], v[80:95]
	v_max3_f32 v33, v64, v65, v66
	v_max3_f32 v33, v33, v67, v68
	v_max3_f32 v33, v33, v69, v70
	v_max3_f32 v33, v33, v71, v72
	v_max3_f32 v33, v33, v73, v74
	v_max3_f32 v33, v33, v75, v76
	v_max3_f32 v33, v33, v77, v78
	v_max_f32_e32 v33, v33, v79
	s_nop 3
	v_max3_f32 v32, v80, v81, v82
	v_max3_f32 v34, v83, v84, v85
	v_max3_f32 v32, v32, v86, v87
	v_max3_f32 v34, v34, v88, v89
	v_max3_f32 v32, v32, v90, v91
	v_max3_f32 v34, v34, v92, v93
	v_max3_f32 v32, v32, v94, v95
	v_max3_f32 v32, v32, v34, v33
	v_mov_b32_e32 v33, v32
	s_nop 1
	v_permlane32_swap_b32_e32 v32, v33
	v_max_f32_e32 v32, v32, v33
	v_cmp_lt_f32_e32 vcc, s80, v32
	s_cbranch_vccz .LBB0_936
	v_max_f32_e32 v48, 0, v32
	v_exp_f32_e64 v32, -v48
	s_nop 0
	v_mov_b32_e32 v49, v32
	v_pk_mul_f32 v[30:31], v[30:31], v[32:33] op_sel_hi:[1,0]
	v_pk_mul_f32 v[28:29], v[28:29], v[32:33] op_sel_hi:[1,0]
	v_pk_mul_f32 v[26:27], v[26:27], v[32:33] op_sel_hi:[1,0]
	v_pk_mul_f32 v[24:25], v[24:25], v[32:33] op_sel_hi:[1,0]
	v_pk_mul_f32 v[22:23], v[22:23], v[32:33] op_sel_hi:[1,0]
	v_pk_mul_f32 v[20:21], v[20:21], v[32:33] op_sel_hi:[1,0]
	v_pk_mul_f32 v[18:19], v[18:19], v[32:33] op_sel_hi:[1,0]
	v_pk_mul_f32 v[14:15], v[14:15], v[32:33] op_sel_hi:[1,0]
	v_pk_mul_f32 v[12:13], v[12:13], v[32:33] op_sel_hi:[1,0]
	v_pk_mul_f32 v[10:11], v[10:11], v[32:33] op_sel_hi:[1,0]
	v_pk_mul_f32 v[8:9], v[8:9], v[32:33] op_sel_hi:[1,0]
	v_pk_mul_f32 v[6:7], v[6:7], v[32:33] op_sel_hi:[1,0]
	v_pk_mul_f32 v[4:5], v[4:5], v[32:33] op_sel_hi:[1,0]
	v_pk_mul_f32 v[2:3], v[2:3], v[32:33] op_sel_hi:[1,0]
	v_pk_mul_f32 v[16:17], v[16:17], v[32:33] op_sel_hi:[1,0]
	v_pk_mul_f32 v[0:1], v[0:1], v[32:33] op_sel_hi:[1,0]
	v_pk_add_f32 v[178:179], v[176:177], v[48:49]
	v_pk_mul_f32 v[32:33], v[176:177], v[48:49]
	v_pk_add_f32 v[80:81], v[80:81], v[48:49] op_sel_hi:[1,0] neg_lo:[0,1] neg_hi:[0,1]
	v_mov_b32_e32 v179, v33
	v_pk_add_f32 v[32:33], v[178:179], 0 neg_lo:[1,1] neg_hi:[1,1]
	v_pk_add_f32 v[64:65], v[64:65], v[48:49] op_sel_hi:[1,0] neg_lo:[0,1] neg_hi:[0,1]
	v_pk_add_f32 v[82:83], v[82:83], v[48:49] op_sel_hi:[1,0] neg_lo:[0,1] neg_hi:[0,1]
	v_pk_add_f32 v[66:67], v[66:67], v[48:49] op_sel_hi:[1,0] neg_lo:[0,1] neg_hi:[0,1]
	v_pk_add_f32 v[84:85], v[84:85], v[48:49] op_sel_hi:[1,0] neg_lo:[0,1] neg_hi:[0,1]
	v_pk_add_f32 v[68:69], v[68:69], v[48:49] op_sel_hi:[1,0] neg_lo:[0,1] neg_hi:[0,1]
	v_pk_add_f32 v[86:87], v[86:87], v[48:49] op_sel_hi:[1,0] neg_lo:[0,1] neg_hi:[0,1]
	v_pk_add_f32 v[70:71], v[70:71], v[48:49] op_sel_hi:[1,0] neg_lo:[0,1] neg_hi:[0,1]
	v_pk_add_f32 v[88:89], v[88:89], v[48:49] op_sel_hi:[1,0] neg_lo:[0,1] neg_hi:[0,1]
	v_pk_add_f32 v[72:73], v[72:73], v[48:49] op_sel_hi:[1,0] neg_lo:[0,1] neg_hi:[0,1]
	v_pk_add_f32 v[90:91], v[90:91], v[48:49] op_sel_hi:[1,0] neg_lo:[0,1] neg_hi:[0,1]
	v_pk_add_f32 v[74:75], v[74:75], v[48:49] op_sel_hi:[1,0] neg_lo:[0,1] neg_hi:[0,1]
	v_pk_add_f32 v[92:93], v[92:93], v[48:49] op_sel_hi:[1,0] neg_lo:[0,1] neg_hi:[0,1]
	v_pk_add_f32 v[76:77], v[76:77], v[48:49] op_sel_hi:[1,0] neg_lo:[0,1] neg_hi:[0,1]
	v_mov_b32_e32 v33, v32
	v_mov_b32_e32 v34, v32
	v_mov_b32_e32 v35, v32
	v_mov_b32_e32 v36, v32
	v_mov_b32_e32 v37, v32
	v_mov_b32_e32 v38, v32
	v_mov_b32_e32 v39, v32
	v_mov_b32_e32 v40, v32
	v_mov_b32_e32 v41, v32
	v_mov_b32_e32 v42, v32
	v_mov_b32_e32 v43, v32
	v_mov_b32_e32 v44, v32
	v_mov_b32_e32 v45, v32
	v_mov_b32_e32 v46, v32
	v_mov_b32_e32 v47, v32
	v_pk_add_f32 v[94:95], v[94:95], v[48:49] op_sel_hi:[1,0] neg_lo:[0,1] neg_hi:[0,1]
	v_pk_add_f32 v[78:79], v[78:79], v[48:49] op_sel_hi:[1,0] neg_lo:[0,1] neg_hi:[0,1]
	v_mov_b32_e32 v48, v32
	v_mov_b32_e32 v49, v32
	v_mov_b32_e32 v50, v32
	v_mov_b32_e32 v51, v32
	v_mov_b32_e32 v52, v32
	v_mov_b32_e32 v53, v32
	v_mov_b32_e32 v54, v32
	v_mov_b32_e32 v55, v32
	v_mov_b32_e32 v56, v32
	v_mov_b32_e32 v57, v32
	v_mov_b32_e32 v58, v32
	v_mov_b32_e32 v59, v32
	v_mov_b32_e32 v60, v32
	v_mov_b32_e32 v61, v32
	v_mov_b32_e32 v62, v32
	v_mov_b32_e32 v63, v32
	v_mov_b32_e32 v176, v178
	s_branch .LBB0_937

.LBB0_959:
	s_or_b64 exec, exec, s[0:1]
	v_lshl_add_u64 v[64:65], s[4:5], 0, v[206:207]
	v_add_co_u32_e32 v64, vcc, 0xa808000, v64
	v_add3_u32 v96, s29, v245, v204
	s_nop 0
	v_addc_co_u32_e32 v65, vcc, 0, v65, vcc
	global_load_dwordx4 v[152:155], v[64:65], off
	global_load_dwordx4 v[156:159], v[64:65], off offset:256
	ds_read_b128 v[64:67], v96
	ds_read_b128 v[68:71], v96 offset:0x1200
	ds_read_b128 v[72:75], v96 offset:32
	ds_read_b128 v[76:79], v96 offset:0x1220
	ds_read_b128 v[160:163], v96 offset:64
	ds_read_b128 v[164:167], v96 offset:0x1240
	ds_read_b128 v[168:171], v96 offset:96
	ds_read_b128 v[172:175], v96 offset:0x1260
	s_nop 0
	s_waitcnt lgkmcnt(7)
	v_mfma_f32_32x32x16_bf16 v[112:127], v[64:67], v[140:143], v[80:95]
	v_add_u32_e32 v64, s29, v246
	v_add3_u32 v247, v64, v244, s87
	s_waitcnt lgkmcnt(6)
	v_mfma_f32_32x32x16_bf16 v[96:111], v[68:71], v[140:143], v[80:95]
	s_waitcnt lgkmcnt(5)
	v_mfma_f32_32x32x16_bf16 v[112:127], v[72:75], v[136:139], v[112:127]
	s_waitcnt lgkmcnt(4)
	v_mfma_f32_32x32x16_bf16 v[96:111], v[76:79], v[136:139], v[96:111]
	s_waitcnt lgkmcnt(3)
	v_mfma_f32_32x32x16_bf16 v[112:127], v[160:163], v[132:135], v[112:127]
	s_waitcnt lgkmcnt(2)
	v_mfma_f32_32x32x16_bf16 v[96:111], v[164:167], v[132:135], v[96:111]
	s_waitcnt lgkmcnt(1)
	v_mfma_f32_32x32x16_bf16 v[112:127], v[168:171], v[128:131], v[112:127]
	s_waitcnt lgkmcnt(0)
	v_mfma_f32_32x32x16_bf16 v[96:111], v[172:175], v[128:131], v[96:111]
	ds_read_b64 v[188:189], v247
	ds_read_b64 v[190:191], v247 offset:16
	ds_read_b64 v[184:185], v247 offset:32
	ds_read_b64 v[186:187], v247 offset:48
	ds_read_b64 v[180:181], v247 offset:64
	ds_read_b64 v[182:183], v247 offset:80
	ds_read_b64 v[176:177], v247 offset:96
	ds_read_b64 v[178:179], v247 offset:112
	ds_read_b64 v[172:173], v247 offset:0x1100
	ds_read_b64 v[174:175], v247 offset:0x1110
	ds_read_b64 v[168:169], v247 offset:0x1120
	ds_read_b64 v[170:171], v247 offset:0x1130
	ds_read_b64 v[164:165], v247 offset:0x1140
	ds_read_b64 v[166:167], v247 offset:0x1150
	ds_read_b64 v[160:161], v247 offset:0x1160
	ds_read_b64 v[162:163], v247 offset:0x1170
	v_max3_f32 v65, v112, v113, v114
	v_max3_f32 v65, v65, v115, v116
	v_max3_f32 v65, v65, v117, v118
	v_max3_f32 v65, v65, v119, v120
	v_max3_f32 v65, v65, v121, v122
	v_max3_f32 v65, v65, v123, v124
	v_max3_f32 v65, v65, v125, v126
	v_max_f32_e32 v65, v65, v127
	v_max3_f32 v64, v96, v97, v98
	v_max3_f32 v66, v99, v100, v101
	v_max3_f32 v64, v64, v102, v103
	v_max3_f32 v66, v66, v104, v105
	v_max3_f32 v64, v64, v106, v107
	v_max3_f32 v66, v66, v108, v109
	v_max3_f32 v64, v64, v110, v111
	v_max3_f32 v64, v64, v66, v65
	v_mov_b32_e32 v65, v64
	s_nop 1
	v_permlane32_swap_b32_e32 v64, v65
	v_max_f32_e32 v64, v64, v65
	v_cmp_lt_f32_e32 vcc, s80, v64
	s_cbranch_vccz .LBB0_961
	v_max_f32_e32 v80, 0, v64
	v_exp_f32_e64 v64, -v80
	s_nop 0
	v_mov_b32_e32 v81, v64
	v_pk_mul_f32 v[14:15], v[14:15], v[64:65] op_sel_hi:[1,0]
	v_pk_mul_f32 v[12:13], v[12:13], v[64:65] op_sel_hi:[1,0]
	v_pk_mul_f32 v[10:11], v[10:11], v[64:65] op_sel_hi:[1,0]
	v_pk_mul_f32 v[8:9], v[8:9], v[64:65] op_sel_hi:[1,0]
	v_pk_mul_f32 v[6:7], v[6:7], v[64:65] op_sel_hi:[1,0]
	v_pk_mul_f32 v[4:5], v[4:5], v[64:65] op_sel_hi:[1,0]
	v_pk_mul_f32 v[2:3], v[2:3], v[64:65] op_sel_hi:[1,0]
	v_pk_mul_f32 v[0:1], v[0:1], v[64:65] op_sel_hi:[1,0]
	v_pk_mul_f32 v[30:31], v[30:31], v[64:65] op_sel_hi:[1,0]
	v_pk_mul_f32 v[28:29], v[28:29], v[64:65] op_sel_hi:[1,0]
	v_pk_mul_f32 v[26:27], v[26:27], v[64:65] op_sel_hi:[1,0]
	v_pk_mul_f32 v[24:25], v[24:25], v[64:65] op_sel_hi:[1,0]
	v_pk_mul_f32 v[22:23], v[22:23], v[64:65] op_sel_hi:[1,0]
	v_pk_mul_f32 v[20:21], v[20:21], v[64:65] op_sel_hi:[1,0]
	v_pk_mul_f32 v[18:19], v[18:19], v[64:65] op_sel_hi:[1,0]
	v_pk_mul_f32 v[16:17], v[16:17], v[64:65] op_sel_hi:[1,0]
	v_pk_mul_f32 v[62:63], v[62:63], v[64:65] op_sel_hi:[1,0]
	v_pk_mul_f32 v[60:61], v[60:61], v[64:65] op_sel_hi:[1,0]
	v_pk_mul_f32 v[58:59], v[58:59], v[64:65] op_sel_hi:[1,0]
	v_pk_mul_f32 v[56:57], v[56:57], v[64:65] op_sel_hi:[1,0]
	v_pk_mul_f32 v[54:55], v[54:55], v[64:65] op_sel_hi:[1,0]
	v_pk_mul_f32 v[52:53], v[52:53], v[64:65] op_sel_hi:[1,0]
	v_pk_mul_f32 v[50:51], v[50:51], v[64:65] op_sel_hi:[1,0]
	v_pk_mul_f32 v[48:49], v[48:49], v[64:65] op_sel_hi:[1,0]
	v_pk_mul_f32 v[46:47], v[46:47], v[64:65] op_sel_hi:[1,0]
	v_pk_mul_f32 v[44:45], v[44:45], v[64:65] op_sel_hi:[1,0]
	v_pk_mul_f32 v[42:43], v[42:43], v[64:65] op_sel_hi:[1,0]
	v_pk_mul_f32 v[40:41], v[40:41], v[64:65] op_sel_hi:[1,0]
	v_pk_mul_f32 v[38:39], v[38:39], v[64:65] op_sel_hi:[1,0]
	v_pk_mul_f32 v[36:37], v[36:37], v[64:65] op_sel_hi:[1,0]
	v_pk_mul_f32 v[34:35], v[34:35], v[64:65] op_sel_hi:[1,0]
	v_pk_mul_f32 v[32:33], v[32:33], v[64:65] op_sel_hi:[1,0]
	v_pk_add_f32 v[214:215], v[212:213], v[80:81]
	v_pk_mul_f32 v[64:65], v[212:213], v[80:81]
	v_pk_add_f32 v[112:113], v[112:113], v[80:81] op_sel_hi:[1,0] neg_lo:[0,1] neg_hi:[0,1]
	v_mov_b32_e32 v215, v65
	v_pk_add_f32 v[64:65], v[214:215], 0 neg_lo:[1,1] neg_hi:[1,1]
	v_pk_add_f32 v[96:97], v[96:97], v[80:81] op_sel_hi:[1,0] neg_lo:[0,1] neg_hi:[0,1]
	v_pk_add_f32 v[114:115], v[114:115], v[80:81] op_sel_hi:[1,0] neg_lo:[0,1] neg_hi:[0,1]
	v_pk_add_f32 v[98:99], v[98:99], v[80:81] op_sel_hi:[1,0] neg_lo:[0,1] neg_hi:[0,1]
	v_pk_add_f32 v[116:117], v[116:117], v[80:81] op_sel_hi:[1,0] neg_lo:[0,1] neg_hi:[0,1]
	v_pk_add_f32 v[100:101], v[100:101], v[80:81] op_sel_hi:[1,0] neg_lo:[0,1] neg_hi:[0,1]
	v_pk_add_f32 v[118:119], v[118:119], v[80:81] op_sel_hi:[1,0] neg_lo:[0,1] neg_hi:[0,1]
	v_pk_add_f32 v[102:103], v[102:103], v[80:81] op_sel_hi:[1,0] neg_lo:[0,1] neg_hi:[0,1]
	v_pk_add_f32 v[120:121], v[120:121], v[80:81] op_sel_hi:[1,0] neg_lo:[0,1] neg_hi:[0,1]
	v_pk_add_f32 v[104:105], v[104:105], v[80:81] op_sel_hi:[1,0] neg_lo:[0,1] neg_hi:[0,1]
	v_pk_add_f32 v[122:123], v[122:123], v[80:81] op_sel_hi:[1,0] neg_lo:[0,1] neg_hi:[0,1]
	v_pk_add_f32 v[106:107], v[106:107], v[80:81] op_sel_hi:[1,0] neg_lo:[0,1] neg_hi:[0,1]
	v_pk_add_f32 v[124:125], v[124:125], v[80:81] op_sel_hi:[1,0] neg_lo:[0,1] neg_hi:[0,1]
	v_pk_add_f32 v[108:109], v[108:109], v[80:81] op_sel_hi:[1,0] neg_lo:[0,1] neg_hi:[0,1]
	v_mov_b32_e32 v65, v64
	v_mov_b32_e32 v66, v64
	v_mov_b32_e32 v67, v64
	v_mov_b32_e32 v68, v64
	v_mov_b32_e32 v69, v64
	v_mov_b32_e32 v70, v64
	v_mov_b32_e32 v71, v64
	v_mov_b32_e32 v72, v64
	v_mov_b32_e32 v73, v64
	v_mov_b32_e32 v74, v64
	v_mov_b32_e32 v75, v64
	v_mov_b32_e32 v76, v64
	v_mov_b32_e32 v77, v64
	v_mov_b32_e32 v78, v64
	v_mov_b32_e32 v79, v64
	v_pk_add_f32 v[126:127], v[126:127], v[80:81] op_sel_hi:[1,0] neg_lo:[0,1] neg_hi:[0,1]
	v_pk_add_f32 v[110:111], v[110:111], v[80:81] op_sel_hi:[1,0] neg_lo:[0,1] neg_hi:[0,1]
	v_mov_b32_e32 v80, v64
	v_mov_b32_e32 v81, v64
	v_mov_b32_e32 v82, v64
	v_mov_b32_e32 v83, v64
	v_mov_b32_e32 v84, v64
	v_mov_b32_e32 v85, v64
	v_mov_b32_e32 v86, v64
	v_mov_b32_e32 v87, v64
	v_mov_b32_e32 v88, v64
	v_mov_b32_e32 v89, v64
	v_mov_b32_e32 v90, v64
	v_mov_b32_e32 v91, v64
	v_mov_b32_e32 v92, v64
	v_mov_b32_e32 v93, v64
	v_mov_b32_e32 v94, v64
	v_mov_b32_e32 v95, v64
	v_mov_b32_e32 v212, v214
	s_branch .LBB0_962

.LBB0_979:
	s_or_b64 exec, exec, s[0:1]
	v_lshl_add_u64 v[64:65], s[4:5], 0, v[204:205]
	v_add_co_u32_e32 v64, vcc, 0xa808000, v64
	v_add3_u32 v96, s9, v246, v192
	s_nop 0
	v_addc_co_u32_e32 v65, vcc, 0, v65, vcc
	global_load_dwordx4 v[152:155], v[64:65], off
	global_load_dwordx4 v[156:159], v[64:65], off offset:256
	ds_read_b128 v[64:67], v96
	ds_read_b128 v[68:71], v96 offset:0x1200
	ds_read_b128 v[72:75], v96 offset:32
	ds_read_b128 v[76:79], v96 offset:0x1220
	ds_read_b128 v[160:163], v96 offset:64
	ds_read_b128 v[164:167], v96 offset:0x1240
	ds_read_b128 v[168:171], v96 offset:96
	ds_read_b128 v[172:175], v96 offset:0x1260
	v_mov_b32_e32 v254, 0xc00
	s_waitcnt lgkmcnt(7)
	v_mfma_f32_32x32x16_bf16 v[112:127], v[64:67], v[140:143], v[80:95]
	v_add_u32_e32 v64, s9, v247
	v_add3_u32 v249, v64, v244, s87
	s_waitcnt lgkmcnt(6)
	v_mfma_f32_32x32x16_bf16 v[96:111], v[68:71], v[140:143], v[80:95]
	s_waitcnt lgkmcnt(5)
	v_mfma_f32_32x32x16_bf16 v[112:127], v[72:75], v[136:139], v[112:127]
	s_waitcnt lgkmcnt(4)
	v_mfma_f32_32x32x16_bf16 v[96:111], v[76:79], v[136:139], v[96:111]
	s_waitcnt lgkmcnt(3)
	v_mfma_f32_32x32x16_bf16 v[112:127], v[160:163], v[132:135], v[112:127]
	s_waitcnt lgkmcnt(2)
	v_mfma_f32_32x32x16_bf16 v[96:111], v[164:167], v[132:135], v[96:111]
	s_waitcnt lgkmcnt(1)
	v_mfma_f32_32x32x16_bf16 v[112:127], v[168:171], v[128:131], v[112:127]
	s_waitcnt lgkmcnt(0)
	v_mfma_f32_32x32x16_bf16 v[96:111], v[172:175], v[128:131], v[96:111]
	ds_read_b64 v[188:189], v249
	ds_read_b64 v[190:191], v249 offset:16
	ds_read_b64 v[184:185], v249 offset:32
	ds_read_b64 v[186:187], v249 offset:48
	ds_read_b64 v[180:181], v249 offset:64
	ds_read_b64 v[182:183], v249 offset:80
	ds_read_b64 v[176:177], v249 offset:96
	ds_read_b64 v[178:179], v249 offset:112
	ds_read_b64 v[172:173], v249 offset:0x1100
	ds_read_b64 v[174:175], v249 offset:0x1110
	ds_read_b64 v[168:169], v249 offset:0x1120
	ds_read_b64 v[170:171], v249 offset:0x1130
	ds_read_b64 v[164:165], v249 offset:0x1140
	ds_read_b64 v[166:167], v249 offset:0x1150
	ds_read_b64 v[160:161], v249 offset:0x1160
	ds_read_b64 v[162:163], v249 offset:0x1170
	v_max3_f32 v65, v112, v113, v114
	v_max3_f32 v65, v65, v115, v116
	v_max3_f32 v65, v65, v117, v118
	v_max3_f32 v65, v65, v119, v120
	v_max3_f32 v65, v65, v121, v122
	v_max3_f32 v65, v65, v123, v124
	v_max3_f32 v65, v65, v125, v126
	v_max_f32_e32 v65, v65, v127
	v_max3_f32 v64, v96, v97, v98
	v_max3_f32 v66, v99, v100, v101
	v_max3_f32 v64, v64, v102, v103
	v_max3_f32 v66, v66, v104, v105
	v_max3_f32 v64, v64, v106, v107
	v_max3_f32 v66, v66, v108, v109
	v_max3_f32 v64, v64, v110, v111
	v_max3_f32 v64, v64, v66, v65
	v_mov_b32_e32 v65, v64
	s_nop 1
	v_permlane32_swap_b32_e32 v64, v65
	v_max_f32_e32 v64, v64, v65
	v_cmp_lt_f32_e32 vcc, s80, v64
	s_cbranch_vccz .LBB0_981
	v_max_f32_e32 v80, 0, v64
	v_exp_f32_e64 v64, -v80
	s_nop 0
	v_mov_b32_e32 v81, v64
	v_pk_mul_f32 v[14:15], v[14:15], v[64:65] op_sel_hi:[1,0]
	v_pk_mul_f32 v[12:13], v[12:13], v[64:65] op_sel_hi:[1,0]
	v_pk_mul_f32 v[10:11], v[10:11], v[64:65] op_sel_hi:[1,0]
	v_pk_mul_f32 v[8:9], v[8:9], v[64:65] op_sel_hi:[1,0]
	v_pk_mul_f32 v[6:7], v[6:7], v[64:65] op_sel_hi:[1,0]
	v_pk_mul_f32 v[4:5], v[4:5], v[64:65] op_sel_hi:[1,0]
	v_pk_mul_f32 v[2:3], v[2:3], v[64:65] op_sel_hi:[1,0]
	v_pk_mul_f32 v[0:1], v[0:1], v[64:65] op_sel_hi:[1,0]
	v_pk_mul_f32 v[62:63], v[62:63], v[64:65] op_sel_hi:[1,0]
	v_pk_mul_f32 v[60:61], v[60:61], v[64:65] op_sel_hi:[1,0]
	v_pk_mul_f32 v[58:59], v[58:59], v[64:65] op_sel_hi:[1,0]
	v_pk_mul_f32 v[56:57], v[56:57], v[64:65] op_sel_hi:[1,0]
	v_pk_mul_f32 v[54:55], v[54:55], v[64:65] op_sel_hi:[1,0]
	v_pk_mul_f32 v[52:53], v[52:53], v[64:65] op_sel_hi:[1,0]
	v_pk_mul_f32 v[50:51], v[50:51], v[64:65] op_sel_hi:[1,0]
	v_pk_mul_f32 v[48:49], v[48:49], v[64:65] op_sel_hi:[1,0]
	v_pk_mul_f32 v[46:47], v[46:47], v[64:65] op_sel_hi:[1,0]
	v_pk_mul_f32 v[44:45], v[44:45], v[64:65] op_sel_hi:[1,0]
	v_pk_mul_f32 v[42:43], v[42:43], v[64:65] op_sel_hi:[1,0]
	v_pk_mul_f32 v[40:41], v[40:41], v[64:65] op_sel_hi:[1,0]
	v_pk_mul_f32 v[38:39], v[38:39], v[64:65] op_sel_hi:[1,0]
	v_pk_mul_f32 v[36:37], v[36:37], v[64:65] op_sel_hi:[1,0]
	v_pk_mul_f32 v[34:35], v[34:35], v[64:65] op_sel_hi:[1,0]
	v_pk_mul_f32 v[32:33], v[32:33], v[64:65] op_sel_hi:[1,0]
	v_pk_mul_f32 v[30:31], v[30:31], v[64:65] op_sel_hi:[1,0]
	v_pk_mul_f32 v[28:29], v[28:29], v[64:65] op_sel_hi:[1,0]
	v_pk_mul_f32 v[26:27], v[26:27], v[64:65] op_sel_hi:[1,0]
	v_pk_mul_f32 v[24:25], v[24:25], v[64:65] op_sel_hi:[1,0]
	v_pk_mul_f32 v[22:23], v[22:23], v[64:65] op_sel_hi:[1,0]
	v_pk_mul_f32 v[20:21], v[20:21], v[64:65] op_sel_hi:[1,0]
	v_pk_mul_f32 v[18:19], v[18:19], v[64:65] op_sel_hi:[1,0]
	v_pk_mul_f32 v[16:17], v[16:17], v[64:65] op_sel_hi:[1,0]
	v_pk_add_f32 v[212:213], v[210:211], v[80:81]
	v_pk_mul_f32 v[64:65], v[210:211], v[80:81]
	v_pk_add_f32 v[112:113], v[112:113], v[80:81] op_sel_hi:[1,0] neg_lo:[0,1] neg_hi:[0,1]
	v_mov_b32_e32 v213, v65
	v_pk_add_f32 v[64:65], v[212:213], 0 neg_lo:[1,1] neg_hi:[1,1]
	v_pk_add_f32 v[96:97], v[96:97], v[80:81] op_sel_hi:[1,0] neg_lo:[0,1] neg_hi:[0,1]
	v_pk_add_f32 v[114:115], v[114:115], v[80:81] op_sel_hi:[1,0] neg_lo:[0,1] neg_hi:[0,1]
	v_pk_add_f32 v[98:99], v[98:99], v[80:81] op_sel_hi:[1,0] neg_lo:[0,1] neg_hi:[0,1]
	v_pk_add_f32 v[116:117], v[116:117], v[80:81] op_sel_hi:[1,0] neg_lo:[0,1] neg_hi:[0,1]
	v_pk_add_f32 v[100:101], v[100:101], v[80:81] op_sel_hi:[1,0] neg_lo:[0,1] neg_hi:[0,1]
	v_pk_add_f32 v[118:119], v[118:119], v[80:81] op_sel_hi:[1,0] neg_lo:[0,1] neg_hi:[0,1]
	v_pk_add_f32 v[102:103], v[102:103], v[80:81] op_sel_hi:[1,0] neg_lo:[0,1] neg_hi:[0,1]
	v_pk_add_f32 v[120:121], v[120:121], v[80:81] op_sel_hi:[1,0] neg_lo:[0,1] neg_hi:[0,1]
	v_pk_add_f32 v[104:105], v[104:105], v[80:81] op_sel_hi:[1,0] neg_lo:[0,1] neg_hi:[0,1]
	v_pk_add_f32 v[122:123], v[122:123], v[80:81] op_sel_hi:[1,0] neg_lo:[0,1] neg_hi:[0,1]
	v_pk_add_f32 v[106:107], v[106:107], v[80:81] op_sel_hi:[1,0] neg_lo:[0,1] neg_hi:[0,1]
	v_pk_add_f32 v[124:125], v[124:125], v[80:81] op_sel_hi:[1,0] neg_lo:[0,1] neg_hi:[0,1]
	v_pk_add_f32 v[108:109], v[108:109], v[80:81] op_sel_hi:[1,0] neg_lo:[0,1] neg_hi:[0,1]
	v_mov_b32_e32 v65, v64
	v_mov_b32_e32 v66, v64
	v_mov_b32_e32 v67, v64
	v_mov_b32_e32 v68, v64
	v_mov_b32_e32 v69, v64
	v_mov_b32_e32 v70, v64
	v_mov_b32_e32 v71, v64
	v_mov_b32_e32 v72, v64
	v_mov_b32_e32 v73, v64
	v_mov_b32_e32 v74, v64
	v_mov_b32_e32 v75, v64
	v_mov_b32_e32 v76, v64
	v_mov_b32_e32 v77, v64
	v_mov_b32_e32 v78, v64
	v_mov_b32_e32 v79, v64
	v_pk_add_f32 v[126:127], v[126:127], v[80:81] op_sel_hi:[1,0] neg_lo:[0,1] neg_hi:[0,1]
	v_pk_add_f32 v[110:111], v[110:111], v[80:81] op_sel_hi:[1,0] neg_lo:[0,1] neg_hi:[0,1]
	v_mov_b32_e32 v80, v64
	v_mov_b32_e32 v81, v64
	v_mov_b32_e32 v82, v64
	v_mov_b32_e32 v83, v64
	v_mov_b32_e32 v84, v64
	v_mov_b32_e32 v85, v64
	v_mov_b32_e32 v86, v64
	v_mov_b32_e32 v87, v64
	v_mov_b32_e32 v88, v64
	v_mov_b32_e32 v89, v64
	v_mov_b32_e32 v90, v64
	v_mov_b32_e32 v91, v64
	v_mov_b32_e32 v92, v64
	v_mov_b32_e32 v93, v64
	v_mov_b32_e32 v94, v64
	v_mov_b32_e32 v95, v64
	v_mov_b32_e32 v210, v212
	s_branch .LBB0_982
